# scan pass 2 items rebalanced: the 12 workgroups with the heaviest attention q-tile pairs hand their scan chunk to the 12 lightest
# speedup vs baseline: 1.0053x; 1.0053x over previous
; DEV int ltid() { int t = threadIdx.x; asm volatile("" : "+v"(t)); return t; }
; DEV void ph_scan2(const Params& p, int item) {
;   const int b = item / NCH, c = item % NCH, ch = ltid() * 4;
;   float H[4] = {0.f, 0.f, 0.f, 0.f};
;   for (int c2 = 0; c2 < c; ++c2) {
;     float4 a = *(const float4*)(p.csA + (size_t)(b * NCH + c2) * 1024 + ch);
;     float4 hh = *(const float4*)(p.csH + (size_t)(b * NCH + c2) * 1024 + ch);
;     H[0] = a.x * H[0] + hh.x; H[1] = a.y * H[1] + hh.y; H[2] = a.z * H[2] + hh.z; H[3] = a.w * H[3] + hh.w;
;   }
;   const size_t row0 = (size_t)(b * S_ + c * CHL);
; #pragma unroll 8
;   for (int t = 0; t < CHL; ++t) {
; __global__ void __launch_bounds__(256, 2) fwd_megakernel(Params p) {
;     ...
;   for (int it = bid; it < B_ * NCH; it += nb) ph_scan2(p, it);
.Lp6_entry:
	v_mov_b32_e32 v1, v0
	s_cmpk_gt_i32 s94, 0x1ff
	s_waitcnt lgkmcnt(0)
	s_barrier
	s_cbranch_scc1 .LBB0_1132
	s_mov_b64 exec, -1
	v_lshlrev_b32_e32 v1, 4, v0
	v_lshlrev_b32_e32 v2, 3, v0
	v_mov_b32_e32 v8, 0x3ba10414
	v_mov_b32_e32 v9, 0xb9c68948
	v_mov_b32_e32 v3, 0x7f800000
	s_mov_b32 s72, 0x378e98ab
	s_mov_b32 s73, 0x3b7cd369
	s_mov_b32 s74, 0xbcc618b2
	s_mov_b32 s75, 0x3dda74e4
	s_mov_b32 s76, 0x3f228afd
	s_mov_b32 s77, 0x3e03c728
	s_mov_b32 s78, 0xbfb8aa3b
	s_mov_b32 s79, 0x42ce8ed0
	s_mov_b32 s80, 0xc2b17218
	s_brev_b32 s81, -2
	s_mov_b32 s50, s94
	s_lshr_b32 s8, s94, 4
	s_cmp_gt_u32 s8, 19
	s_cbranch_scc1 .Lsc_end

; DEV unsigned pack2(float a, float b) { float2v v = {a, b}; return __builtin_bit_cast(unsigned, __builtin_convertvector(v, bf16x2v)); }
; DEV float bflo(unsigned u) { return __uint_as_float(u << 16); }
; DEV float bfhi(unsigned u) { return __uint_as_float(u & 0xffff0000u); }
; DEV float gelu_exact(float v) { return 0.5f * v * (1.f + erff(v * 0.7071067811865476f)); }
; DEV void ph_scan2(const Params& p, int item) {
;     ...
; #pragma unroll 8
;   for (int t = 0; t < CHL; ++t) {
;     float4 a = *(const float4*)(p.a_arr + (row0 + t) * 1024 + ch);
;     float4 bb = *(const float4*)(p.b_arr + (row0 + t) * 1024 + ch);
;     u32x2 xg = *(const u32x2*)(p.z + (row0 + t) * ZLD + CXG + ch);
;     H[0] = a.x * H[0] + bb.x; H[1] = a.y * H[1] + bb.y; H[2] = a.z * H[2] + bb.z; H[3] = a.w * H[3] + bb.w;
;     u32x2 pk;
;     pk[0] = pack2(gelu_exact(bflo(xg[0])) * H[0], gelu_exact(bfhi(xg[0])) * H[1]);
;     pk[1] = pack2(gelu_exact(bflo(xg[1])) * H[2], gelu_exact(bfhi(xg[1])) * H[3]);
;     *(u32x2*)(p.orn + (row0 + t) * 1024 + ch) = pk;
;   }
.Lsc_main:
	global_load_dwordx4 v[80:83], v1, s[2:3] sc0 sc1 nt
	global_load_dwordx4 v[84:87], v1, s[4:5] sc0 sc1 nt
	global_load_dwordx2 v[88:89], v2, s[6:7] sc0 sc1 nt
	s_add_u32 s2, s2, 0x1000
	s_addc_u32 s3, s3, 0
	s_add_u32 s4, s4, 0x1000
	s_addc_u32 s5, s5, 0
	s_add_u32 s6, s6, 0x2500
	s_addc_u32 s7, s7, 0
	global_load_dwordx4 v[90:93], v1, s[2:3] sc0 sc1 nt
	global_load_dwordx4 v[94:97], v1, s[4:5] sc0 sc1 nt
	global_load_dwordx2 v[98:99], v2, s[6:7] sc0 sc1 nt
	s_add_u32 s2, s2, 0x1000
	s_addc_u32 s3, s3, 0
	s_add_u32 s4, s4, 0x1000
	s_addc_u32 s5, s5, 0
	s_add_u32 s6, s6, 0x2500
	s_addc_u32 s7, s7, 0
	global_load_dwordx4 v[100:103], v1, s[2:3] sc0 sc1 nt
	global_load_dwordx4 v[104:107], v1, s[4:5] sc0 sc1 nt
	global_load_dwordx2 v[108:109], v2, s[6:7] sc0 sc1 nt
	s_add_u32 s2, s2, 0x1000
	s_addc_u32 s3, s3, 0
	s_add_u32 s4, s4, 0x1000
	s_addc_u32 s5, s5, 0
	s_add_u32 s6, s6, 0x2500
	s_addc_u32 s7, s7, 0
	global_load_dwordx4 v[110:113], v1, s[2:3] sc0 sc1 nt
	global_load_dwordx4 v[114:117], v1, s[4:5] sc0 sc1 nt
	global_load_dwordx2 v[118:119], v2, s[6:7] sc0 sc1 nt
	s_add_u32 s2, s2, 0x1000
	s_addc_u32 s3, s3, 0
	s_add_u32 s4, s4, 0x1000
	s_addc_u32 s5, s5, 0
	s_add_u32 s6, s6, 0x2500
	s_addc_u32 s7, s7, 0
	global_load_dwordx4 v[120:123], v1, s[2:3] sc0 sc1 nt
	global_load_dwordx4 v[124:127], v1, s[4:5] sc0 sc1 nt
	global_load_dwordx2 v[128:129], v2, s[6:7] sc0 sc1 nt
	s_add_u32 s2, s2, 0x1000
	s_addc_u32 s3, s3, 0
	s_add_u32 s4, s4, 0x1000
	s_addc_u32 s5, s5, 0
	s_add_u32 s6, s6, 0x2500
	s_addc_u32 s7, s7, 0
	global_load_dwordx4 v[130:133], v1, s[2:3] sc0 sc1 nt
	global_load_dwordx4 v[134:137], v1, s[4:5] sc0 sc1 nt
	global_load_dwordx2 v[138:139], v2, s[6:7] sc0 sc1 nt
	s_add_u32 s2, s2, 0x1000
	s_addc_u32 s3, s3, 0
	s_add_u32 s4, s4, 0x1000
	s_addc_u32 s5, s5, 0
	s_add_u32 s6, s6, 0x2500
	s_addc_u32 s7, s7, 0
	global_load_dwordx4 v[140:143], v1, s[2:3] sc0 sc1 nt
	global_load_dwordx4 v[144:147], v1, s[4:5] sc0 sc1 nt
	global_load_dwordx2 v[148:149], v2, s[6:7] sc0 sc1 nt
	s_add_u32 s2, s2, 0x1000
	s_addc_u32 s3, s3, 0
	s_add_u32 s4, s4, 0x1000
	s_addc_u32 s5, s5, 0
	s_add_u32 s6, s6, 0x2500
	s_addc_u32 s7, s7, 0
	global_load_dwordx4 v[150:153], v1, s[2:3] sc0 sc1 nt
	global_load_dwordx4 v[154:157], v1, s[4:5] sc0 sc1 nt
	global_load_dwordx2 v[158:159], v2, s[6:7] sc0 sc1 nt
	s_add_u32 s2, s2, 0x1000
	s_addc_u32 s3, s3, 0
	s_add_u32 s4, s4, 0x1000
	s_addc_u32 s5, s5, 0
	s_add_u32 s6, s6, 0x2500
	s_addc_u32 s7, s7, 0
	s_waitcnt vmcnt(21)
	v_fma_f32 v4, v80, v4, v84
	v_fma_f32 v5, v81, v5, v85
	v_fma_f32 v6, v82, v6, v86
	v_fma_f32 v7, v83, v7, v87
	v_lshlrev_b32_e32 v168, 16, v88
	v_and_b32_e32 v169, 0xffff0000, v88
	v_lshlrev_b32_e32 v170, 16, v89
	v_and_b32_e32 v171, 0xffff0000, v89
	v_mul_f32_e32 v160, 0x3f3504f3, v168
	v_mul_f32_e32 v161, v160, v160
	v_fmamk_f32 v162, v161, 0xba1345e1, v8
	v_fmaak_f32 v162, v161, v162, 0xbcdac9b8
	v_fmaak_f32 v162, v161, v162, 0x3de703be
	v_fmaak_f32 v162, v161, v162, 0xbec09330
	v_fmaak_f32 v161, v161, v162, 0x3e0375d0
	v_fma_f32 v165, |v160|, v161, |v160|
	v_fma_f32 v161, |v160|, s72, v9
	v_fma_f32 v161, |v160|, v161, s73
	v_fma_f32 v161, |v160|, v161, s74
	v_fma_f32 v161, |v160|, v161, s75
	v_fma_f32 v161, |v160|, v161, s76
	v_fma_f32 v161, |v160|, v161, s77
	v_fma_f32 v161, |v160|, v161, |v160|
	v_mul_f32_e32 v162, 0xbfb8aa3b, v161
	v_fma_f32 v163, v161, s78, -v162
	v_rndne_f32_e32 v164, v162
	v_fmac_f32_e32 v163, 0xb2a5705f, v161
	v_sub_f32_e32 v162, v162, v164
	v_add_f32_e32 v162, v162, v163
	v_cvt_i32_f32_e32 v163, v164
	v_exp_f32_e32 v162, v162
	v_cmp_nlt_f32_e32 vcc, s79, v161
	v_ldexp_f32 v162, v162, v163
	s_nop 0
	v_cndmask_b32_e32 v162, 0, v162, vcc
	v_cmp_ngt_f32_e32 vcc, s80, v161
	s_nop 1
	v_cndmask_b32_e32 v161, v3, v162, vcc
	v_sub_f32_e32 v166, 1.0, v161
	v_cmp_lt_f32_e64 vcc, |v160|, 1.0
	s_nop 1
	v_cndmask_b32_e32 v165, v166, v165, vcc
	v_bfi_b32 v165, s81, v165, v160
	v_mul_f32_e32 v161, 0.5, v168
	v_add_f32_e32 v165, 1.0, v165
	v_mul_f32_e32 v161, v161, v165
	v_mul_f32_e32 v176, v161, v4
	v_mul_f32_e32 v160, 0x3f3504f3, v169
	v_mul_f32_e32 v161, v160, v160
	v_fmamk_f32 v162, v161, 0xba1345e1, v8
	v_fmaak_f32 v162, v161, v162, 0xbcdac9b8
	v_fmaak_f32 v162, v161, v162, 0x3de703be
	v_fmaak_f32 v162, v161, v162, 0xbec09330
	v_fmaak_f32 v161, v161, v162, 0x3e0375d0
	v_fma_f32 v165, |v160|, v161, |v160|
	v_fma_f32 v161, |v160|, s72, v9
	v_fma_f32 v161, |v160|, v161, s73
	v_fma_f32 v161, |v160|, v161, s74
	v_fma_f32 v161, |v160|, v161, s75
	v_fma_f32 v161, |v160|, v161, s76
	v_fma_f32 v161, |v160|, v161, s77
	v_fma_f32 v161, |v160|, v161, |v160|
	v_mul_f32_e32 v162, 0xbfb8aa3b, v161
	v_fma_f32 v163, v161, s78, -v162
	v_rndne_f32_e32 v164, v162
	v_fmac_f32_e32 v163, 0xb2a5705f, v161
	v_sub_f32_e32 v162, v162, v164
	v_add_f32_e32 v162, v162, v163
	v_cvt_i32_f32_e32 v163, v164
	v_exp_f32_e32 v162, v162
	v_cmp_nlt_f32_e32 vcc, s79, v161
	v_ldexp_f32 v162, v162, v163
	s_nop 0
	v_cndmask_b32_e32 v162, 0, v162, vcc
	v_cmp_ngt_f32_e32 vcc, s80, v161
	s_nop 1
	v_cndmask_b32_e32 v161, v3, v162, vcc
	v_sub_f32_e32 v166, 1.0, v161
	v_cmp_lt_f32_e64 vcc, |v160|, 1.0
	s_nop 1
	v_cndmask_b32_e32 v165, v166, v165, vcc
	v_bfi_b32 v165, s81, v165, v160
	v_mul_f32_e32 v161, 0.5, v169
	v_add_f32_e32 v165, 1.0, v165
	v_mul_f32_e32 v161, v161, v165
	v_mul_f32_e32 v177, v161, v5
	v_mul_f32_e32 v160, 0x3f3504f3, v170
	v_mul_f32_e32 v161, v160, v160
	v_fmamk_f32 v162, v161, 0xba1345e1, v8
	v_fmaak_f32 v162, v161, v162, 0xbcdac9b8
	v_fmaak_f32 v162, v161, v162, 0x3de703be
	v_fmaak_f32 v162, v161, v162, 0xbec09330
	v_fmaak_f32 v161, v161, v162, 0x3e0375d0
	v_fma_f32 v165, |v160|, v161, |v160|
; DEV unsigned pack2(float a, float b) { float2v v = {a, b}; return __builtin_bit_cast(unsigned, __builtin_convertvector(v, bf16x2v)); }
; DEV float bflo(unsigned u) { return __uint_as_float(u << 16); }
; DEV float bfhi(unsigned u) { return __uint_as_float(u & 0xffff0000u); }
; DEV float gelu_exact(float v) { return 0.5f * v * (1.f + erff(v * 0.7071067811865476f)); }
; DEV void ph_scan2(const Params& p, int item) {
;     ...
; #pragma unroll 8
;   for (int t = 0; t < CHL; ++t) {
;     float4 a = *(const float4*)(p.a_arr + (row0 + t) * 1024 + ch);
;     float4 bb = *(const float4*)(p.b_arr + (row0 + t) * 1024 + ch);
;     u32x2 xg = *(const u32x2*)(p.z + (row0 + t) * ZLD + CXG + ch);
;     H[0] = a.x * H[0] + bb.x; H[1] = a.y * H[1] + bb.y; H[2] = a.z * H[2] + bb.z; H[3] = a.w * H[3] + bb.w;
;     u32x2 pk;
;     pk[0] = pack2(gelu_exact(bflo(xg[0])) * H[0], gelu_exact(bfhi(xg[0])) * H[1]);
;     pk[1] = pack2(gelu_exact(bflo(xg[1])) * H[2], gelu_exact(bfhi(xg[1])) * H[3]);
;     *(u32x2*)(p.orn + (row0 + t) * 1024 + ch) = pk;
;   }
	v_fma_f32 v161, |v160|, s72, v9
	v_fma_f32 v161, |v160|, v161, s73
	v_fma_f32 v161, |v160|, v161, s74
	v_fma_f32 v161, |v160|, v161, s75
	v_fma_f32 v161, |v160|, v161, s76
	v_fma_f32 v161, |v160|, v161, s77
	v_fma_f32 v161, |v160|, v161, |v160|
	v_mul_f32_e32 v162, 0xbfb8aa3b, v161
	v_fma_f32 v163, v161, s78, -v162
	v_rndne_f32_e32 v164, v162
	v_fmac_f32_e32 v163, 0xb2a5705f, v161
	v_sub_f32_e32 v162, v162, v164
	v_add_f32_e32 v162, v162, v163
	v_cvt_i32_f32_e32 v163, v164
	v_exp_f32_e32 v162, v162
	v_cmp_nlt_f32_e32 vcc, s79, v161
	v_ldexp_f32 v162, v162, v163
	s_nop 0
	v_cndmask_b32_e32 v162, 0, v162, vcc
	v_cmp_ngt_f32_e32 vcc, s80, v161
	s_nop 1
	v_cndmask_b32_e32 v161, v3, v162, vcc
	v_sub_f32_e32 v166, 1.0, v161
	v_cmp_lt_f32_e64 vcc, |v160|, 1.0
	s_nop 1
	v_cndmask_b32_e32 v165, v166, v165, vcc
	v_bfi_b32 v165, s81, v165, v160
	v_mul_f32_e32 v161, 0.5, v170
	v_add_f32_e32 v165, 1.0, v165
	v_mul_f32_e32 v161, v161, v165
	v_mul_f32_e32 v178, v161, v6
	v_mul_f32_e32 v160, 0x3f3504f3, v171
	v_mul_f32_e32 v161, v160, v160
	v_fmamk_f32 v162, v161, 0xba1345e1, v8
	v_fmaak_f32 v162, v161, v162, 0xbcdac9b8
	v_fmaak_f32 v162, v161, v162, 0x3de703be
	v_fmaak_f32 v162, v161, v162, 0xbec09330
	v_fmaak_f32 v161, v161, v162, 0x3e0375d0
	v_fma_f32 v165, |v160|, v161, |v160|
	v_fma_f32 v161, |v160|, s72, v9
	v_fma_f32 v161, |v160|, v161, s73
	v_fma_f32 v161, |v160|, v161, s74
	v_fma_f32 v161, |v160|, v161, s75
	v_fma_f32 v161, |v160|, v161, s76
	v_fma_f32 v161, |v160|, v161, s77
	v_fma_f32 v161, |v160|, v161, |v160|
	v_mul_f32_e32 v162, 0xbfb8aa3b, v161
	v_fma_f32 v163, v161, s78, -v162
	v_rndne_f32_e32 v164, v162
	v_fmac_f32_e32 v163, 0xb2a5705f, v161
	v_sub_f32_e32 v162, v162, v164
	v_add_f32_e32 v162, v162, v163
	v_cvt_i32_f32_e32 v163, v164
	v_exp_f32_e32 v162, v162
	v_cmp_nlt_f32_e32 vcc, s79, v161
	v_ldexp_f32 v162, v162, v163
	s_nop 0
	v_cndmask_b32_e32 v162, 0, v162, vcc
	v_cmp_ngt_f32_e32 vcc, s80, v161
	s_nop 1
	v_cndmask_b32_e32 v161, v3, v162, vcc
	v_sub_f32_e32 v166, 1.0, v161
	v_cmp_lt_f32_e64 vcc, |v160|, 1.0
	s_nop 1
	v_cndmask_b32_e32 v165, v166, v165, vcc
	v_bfi_b32 v165, s81, v165, v160
	v_mul_f32_e32 v161, 0.5, v171
	v_add_f32_e32 v165, 1.0, v165
	v_mul_f32_e32 v161, v161, v165
	v_mul_f32_e32 v179, v161, v7
	v_cvt_pk_bf16_f32 v180, v176, v177
	v_cvt_pk_bf16_f32 v181, v178, v179
	global_store_dwordx2 v2, v[180:181], s[34:35]
	s_add_u32 s34, s34, 0x800
	s_addc_u32 s35, s35, 0
	s_waitcnt vmcnt(19)
	v_fma_f32 v4, v90, v4, v94
	v_fma_f32 v5, v91, v5, v95
	v_fma_f32 v6, v92, v6, v96
	v_fma_f32 v7, v93, v7, v97
	v_lshlrev_b32_e32 v168, 16, v98
	v_and_b32_e32 v169, 0xffff0000, v98
	v_lshlrev_b32_e32 v170, 16, v99
	v_and_b32_e32 v171, 0xffff0000, v99
	v_mul_f32_e32 v160, 0x3f3504f3, v168
	v_mul_f32_e32 v161, v160, v160
	v_fmamk_f32 v162, v161, 0xba1345e1, v8
	v_fmaak_f32 v162, v161, v162, 0xbcdac9b8
	v_fmaak_f32 v162, v161, v162, 0x3de703be
	v_fmaak_f32 v162, v161, v162, 0xbec09330
	v_fmaak_f32 v161, v161, v162, 0x3e0375d0
	v_fma_f32 v165, |v160|, v161, |v160|
	v_fma_f32 v161, |v160|, s72, v9
	v_fma_f32 v161, |v160|, v161, s73
	v_fma_f32 v161, |v160|, v161, s74
	v_fma_f32 v161, |v160|, v161, s75
	v_fma_f32 v161, |v160|, v161, s76
	v_fma_f32 v161, |v160|, v161, s77
	v_fma_f32 v161, |v160|, v161, |v160|
	v_mul_f32_e32 v162, 0xbfb8aa3b, v161
	v_fma_f32 v163, v161, s78, -v162
	v_rndne_f32_e32 v164, v162
	v_fmac_f32_e32 v163, 0xb2a5705f, v161
	v_sub_f32_e32 v162, v162, v164
	v_add_f32_e32 v162, v162, v163
	v_cvt_i32_f32_e32 v163, v164
	v_exp_f32_e32 v162, v162
	v_cmp_nlt_f32_e32 vcc, s79, v161
	v_ldexp_f32 v162, v162, v163
	s_nop 0
	v_cndmask_b32_e32 v162, 0, v162, vcc
	v_cmp_ngt_f32_e32 vcc, s80, v161
	s_nop 1
	v_cndmask_b32_e32 v161, v3, v162, vcc
	v_sub_f32_e32 v166, 1.0, v161
	v_cmp_lt_f32_e64 vcc, |v160|, 1.0
	s_nop 1
	v_cndmask_b32_e32 v165, v166, v165, vcc
	v_bfi_b32 v165, s81, v165, v160
	v_mul_f32_e32 v161, 0.5, v168
	v_add_f32_e32 v165, 1.0, v165
	v_mul_f32_e32 v161, v161, v165
	v_mul_f32_e32 v176, v161, v4
	v_mul_f32_e32 v160, 0x3f3504f3, v169
	v_mul_f32_e32 v161, v160, v160
	v_fmamk_f32 v162, v161, 0xba1345e1, v8
	v_fmaak_f32 v162, v161, v162, 0xbcdac9b8
	v_fmaak_f32 v162, v161, v162, 0x3de703be
	v_fmaak_f32 v162, v161, v162, 0xbec09330
	v_fmaak_f32 v161, v161, v162, 0x3e0375d0
	v_fma_f32 v165, |v160|, v161, |v160|
	v_fma_f32 v161, |v160|, s72, v9
	v_fma_f32 v161, |v160|, v161, s73
	v_fma_f32 v161, |v160|, v161, s74
	v_fma_f32 v161, |v160|, v161, s75
	v_fma_f32 v161, |v160|, v161, s76
	v_fma_f32 v161, |v160|, v161, s77
	v_fma_f32 v161, |v160|, v161, |v160|
	v_mul_f32_e32 v162, 0xbfb8aa3b, v161
	v_fma_f32 v163, v161, s78, -v162
	v_rndne_f32_e32 v164, v162
	v_fmac_f32_e32 v163, 0xb2a5705f, v161
	v_sub_f32_e32 v162, v162, v164
	v_add_f32_e32 v162, v162, v163
	v_cvt_i32_f32_e32 v163, v164
	v_exp_f32_e32 v162, v162
	v_cmp_nlt_f32_e32 vcc, s79, v161
	v_ldexp_f32 v162, v162, v163
	s_nop 0
	v_cndmask_b32_e32 v162, 0, v162, vcc
	v_cmp_ngt_f32_e32 vcc, s80, v161
	s_nop 1
	v_cndmask_b32_e32 v161, v3, v162, vcc
	v_sub_f32_e32 v166, 1.0, v161
	v_cmp_lt_f32_e64 vcc, |v160|, 1.0
	s_nop 1
	v_cndmask_b32_e32 v165, v166, v165, vcc
	v_bfi_b32 v165, s81, v165, v160
	v_mul_f32_e32 v161, 0.5, v169
	v_add_f32_e32 v165, 1.0, v165
	v_mul_f32_e32 v161, v161, v165
	v_mul_f32_e32 v177, v161, v5
	v_mul_f32_e32 v160, 0x3f3504f3, v170
	v_mul_f32_e32 v161, v160, v160
	v_fmamk_f32 v162, v161, 0xba1345e1, v8
	v_fmaak_f32 v162, v161, v162, 0xbcdac9b8
	v_fmaak_f32 v162, v161, v162, 0x3de703be
	v_fmaak_f32 v162, v161, v162, 0xbec09330
	v_fmaak_f32 v161, v161, v162, 0x3e0375d0
	v_fma_f32 v165, |v160|, v161, |v160|
	v_fma_f32 v161, |v160|, s72, v9
; DEV unsigned pack2(float a, float b) { float2v v = {a, b}; return __builtin_bit_cast(unsigned, __builtin_convertvector(v, bf16x2v)); }
; DEV float bflo(unsigned u) { return __uint_as_float(u << 16); }
; DEV float bfhi(unsigned u) { return __uint_as_float(u & 0xffff0000u); }
; DEV float gelu_exact(float v) { return 0.5f * v * (1.f + erff(v * 0.7071067811865476f)); }
; DEV void ph_scan2(const Params& p, int item) {
;     ...
; #pragma unroll 8
;   for (int t = 0; t < CHL; ++t) {
;     float4 a = *(const float4*)(p.a_arr + (row0 + t) * 1024 + ch);
;     float4 bb = *(const float4*)(p.b_arr + (row0 + t) * 1024 + ch);
;     u32x2 xg = *(const u32x2*)(p.z + (row0 + t) * ZLD + CXG + ch);
;     H[0] = a.x * H[0] + bb.x; H[1] = a.y * H[1] + bb.y; H[2] = a.z * H[2] + bb.z; H[3] = a.w * H[3] + bb.w;
;     u32x2 pk;
;     pk[0] = pack2(gelu_exact(bflo(xg[0])) * H[0], gelu_exact(bfhi(xg[0])) * H[1]);
;     pk[1] = pack2(gelu_exact(bflo(xg[1])) * H[2], gelu_exact(bfhi(xg[1])) * H[3]);
;     *(u32x2*)(p.orn + (row0 + t) * 1024 + ch) = pk;
;   }
	v_fma_f32 v161, |v160|, v161, s73
	v_fma_f32 v161, |v160|, v161, s74
	v_fma_f32 v161, |v160|, v161, s75
	v_fma_f32 v161, |v160|, v161, s76
	v_fma_f32 v161, |v160|, v161, s77
	v_fma_f32 v161, |v160|, v161, |v160|
	v_mul_f32_e32 v162, 0xbfb8aa3b, v161
	v_fma_f32 v163, v161, s78, -v162
	v_rndne_f32_e32 v164, v162
	v_fmac_f32_e32 v163, 0xb2a5705f, v161
	v_sub_f32_e32 v162, v162, v164
	v_add_f32_e32 v162, v162, v163
	v_cvt_i32_f32_e32 v163, v164
	v_exp_f32_e32 v162, v162
	v_cmp_nlt_f32_e32 vcc, s79, v161
	v_ldexp_f32 v162, v162, v163
	s_nop 0
	v_cndmask_b32_e32 v162, 0, v162, vcc
	v_cmp_ngt_f32_e32 vcc, s80, v161
	s_nop 1
	v_cndmask_b32_e32 v161, v3, v162, vcc
	v_sub_f32_e32 v166, 1.0, v161
	v_cmp_lt_f32_e64 vcc, |v160|, 1.0
	s_nop 1
	v_cndmask_b32_e32 v165, v166, v165, vcc
	v_bfi_b32 v165, s81, v165, v160
	v_mul_f32_e32 v161, 0.5, v170
	v_add_f32_e32 v165, 1.0, v165
	v_mul_f32_e32 v161, v161, v165
	v_mul_f32_e32 v178, v161, v6
	v_mul_f32_e32 v160, 0x3f3504f3, v171
	v_mul_f32_e32 v161, v160, v160
	v_fmamk_f32 v162, v161, 0xba1345e1, v8
	v_fmaak_f32 v162, v161, v162, 0xbcdac9b8
	v_fmaak_f32 v162, v161, v162, 0x3de703be
	v_fmaak_f32 v162, v161, v162, 0xbec09330
	v_fmaak_f32 v161, v161, v162, 0x3e0375d0
	v_fma_f32 v165, |v160|, v161, |v160|
	v_fma_f32 v161, |v160|, s72, v9
	v_fma_f32 v161, |v160|, v161, s73
	v_fma_f32 v161, |v160|, v161, s74
	v_fma_f32 v161, |v160|, v161, s75
	v_fma_f32 v161, |v160|, v161, s76
	v_fma_f32 v161, |v160|, v161, s77
	v_fma_f32 v161, |v160|, v161, |v160|
	v_mul_f32_e32 v162, 0xbfb8aa3b, v161
	v_fma_f32 v163, v161, s78, -v162
	v_rndne_f32_e32 v164, v162
	v_fmac_f32_e32 v163, 0xb2a5705f, v161
	v_sub_f32_e32 v162, v162, v164
	v_add_f32_e32 v162, v162, v163
	v_cvt_i32_f32_e32 v163, v164
	v_exp_f32_e32 v162, v162
	v_cmp_nlt_f32_e32 vcc, s79, v161
	v_ldexp_f32 v162, v162, v163
	s_nop 0
	v_cndmask_b32_e32 v162, 0, v162, vcc
	v_cmp_ngt_f32_e32 vcc, s80, v161
	s_nop 1
	v_cndmask_b32_e32 v161, v3, v162, vcc
	v_sub_f32_e32 v166, 1.0, v161
	v_cmp_lt_f32_e64 vcc, |v160|, 1.0
	s_nop 1
	v_cndmask_b32_e32 v165, v166, v165, vcc
	v_bfi_b32 v165, s81, v165, v160
	v_mul_f32_e32 v161, 0.5, v171
	v_add_f32_e32 v165, 1.0, v165
	v_mul_f32_e32 v161, v161, v165
	v_mul_f32_e32 v179, v161, v7
	v_cvt_pk_bf16_f32 v180, v176, v177
	v_cvt_pk_bf16_f32 v181, v178, v179
	global_store_dwordx2 v2, v[180:181], s[34:35]
	s_add_u32 s34, s34, 0x800
	s_addc_u32 s35, s35, 0
	s_waitcnt vmcnt(17)
	v_fma_f32 v4, v100, v4, v104
	v_fma_f32 v5, v101, v5, v105
	v_fma_f32 v6, v102, v6, v106
	v_fma_f32 v7, v103, v7, v107
	v_lshlrev_b32_e32 v168, 16, v108
	v_and_b32_e32 v169, 0xffff0000, v108
	v_lshlrev_b32_e32 v170, 16, v109
	v_and_b32_e32 v171, 0xffff0000, v109
	v_mul_f32_e32 v160, 0x3f3504f3, v168
	v_mul_f32_e32 v161, v160, v160
	v_fmamk_f32 v162, v161, 0xba1345e1, v8
	v_fmaak_f32 v162, v161, v162, 0xbcdac9b8
	v_fmaak_f32 v162, v161, v162, 0x3de703be
	v_fmaak_f32 v162, v161, v162, 0xbec09330
	v_fmaak_f32 v161, v161, v162, 0x3e0375d0
	v_fma_f32 v165, |v160|, v161, |v160|
	v_fma_f32 v161, |v160|, s72, v9
	v_fma_f32 v161, |v160|, v161, s73
	v_fma_f32 v161, |v160|, v161, s74
	v_fma_f32 v161, |v160|, v161, s75
	v_fma_f32 v161, |v160|, v161, s76
	v_fma_f32 v161, |v160|, v161, s77
	v_fma_f32 v161, |v160|, v161, |v160|
	v_mul_f32_e32 v162, 0xbfb8aa3b, v161
	v_fma_f32 v163, v161, s78, -v162
	v_rndne_f32_e32 v164, v162
	v_fmac_f32_e32 v163, 0xb2a5705f, v161
	v_sub_f32_e32 v162, v162, v164
	v_add_f32_e32 v162, v162, v163
	v_cvt_i32_f32_e32 v163, v164
	v_exp_f32_e32 v162, v162
	v_cmp_nlt_f32_e32 vcc, s79, v161
	v_ldexp_f32 v162, v162, v163
	s_nop 0
	v_cndmask_b32_e32 v162, 0, v162, vcc
	v_cmp_ngt_f32_e32 vcc, s80, v161
	s_nop 1
	v_cndmask_b32_e32 v161, v3, v162, vcc
	v_sub_f32_e32 v166, 1.0, v161
	v_cmp_lt_f32_e64 vcc, |v160|, 1.0
	s_nop 1
	v_cndmask_b32_e32 v165, v166, v165, vcc
	v_bfi_b32 v165, s81, v165, v160
	v_mul_f32_e32 v161, 0.5, v168
	v_add_f32_e32 v165, 1.0, v165
	v_mul_f32_e32 v161, v161, v165
	v_mul_f32_e32 v176, v161, v4
	v_mul_f32_e32 v160, 0x3f3504f3, v169
	v_mul_f32_e32 v161, v160, v160
	v_fmamk_f32 v162, v161, 0xba1345e1, v8
	v_fmaak_f32 v162, v161, v162, 0xbcdac9b8
	v_fmaak_f32 v162, v161, v162, 0x3de703be
	v_fmaak_f32 v162, v161, v162, 0xbec09330
	v_fmaak_f32 v161, v161, v162, 0x3e0375d0
	v_fma_f32 v165, |v160|, v161, |v160|
	v_fma_f32 v161, |v160|, s72, v9
	v_fma_f32 v161, |v160|, v161, s73
	v_fma_f32 v161, |v160|, v161, s74
	v_fma_f32 v161, |v160|, v161, s75
	v_fma_f32 v161, |v160|, v161, s76
	v_fma_f32 v161, |v160|, v161, s77
	v_fma_f32 v161, |v160|, v161, |v160|
	v_mul_f32_e32 v162, 0xbfb8aa3b, v161
	v_fma_f32 v163, v161, s78, -v162
	v_rndne_f32_e32 v164, v162
	v_fmac_f32_e32 v163, 0xb2a5705f, v161
	v_sub_f32_e32 v162, v162, v164
	v_add_f32_e32 v162, v162, v163
	v_cvt_i32_f32_e32 v163, v164
	v_exp_f32_e32 v162, v162
	v_cmp_nlt_f32_e32 vcc, s79, v161
	v_ldexp_f32 v162, v162, v163
	s_nop 0
	v_cndmask_b32_e32 v162, 0, v162, vcc
	v_cmp_ngt_f32_e32 vcc, s80, v161
	s_nop 1
	v_cndmask_b32_e32 v161, v3, v162, vcc
	v_sub_f32_e32 v166, 1.0, v161
	v_cmp_lt_f32_e64 vcc, |v160|, 1.0
	s_nop 1
	v_cndmask_b32_e32 v165, v166, v165, vcc
	v_bfi_b32 v165, s81, v165, v160
	v_mul_f32_e32 v161, 0.5, v169
	v_add_f32_e32 v165, 1.0, v165
	v_mul_f32_e32 v161, v161, v165
	v_mul_f32_e32 v177, v161, v5
	v_mul_f32_e32 v160, 0x3f3504f3, v170
	v_mul_f32_e32 v161, v160, v160
	v_fmamk_f32 v162, v161, 0xba1345e1, v8
	v_fmaak_f32 v162, v161, v162, 0xbcdac9b8
	v_fmaak_f32 v162, v161, v162, 0x3de703be
	v_fmaak_f32 v162, v161, v162, 0xbec09330
	v_fmaak_f32 v161, v161, v162, 0x3e0375d0
	v_fma_f32 v165, |v160|, v161, |v160|
	v_fma_f32 v161, |v160|, s72, v9
	v_fma_f32 v161, |v160|, v161, s73
; DEV unsigned pack2(float a, float b) { float2v v = {a, b}; return __builtin_bit_cast(unsigned, __builtin_convertvector(v, bf16x2v)); }
; DEV float bflo(unsigned u) { return __uint_as_float(u << 16); }
; DEV float bfhi(unsigned u) { return __uint_as_float(u & 0xffff0000u); }
; DEV float gelu_exact(float v) { return 0.5f * v * (1.f + erff(v * 0.7071067811865476f)); }
; DEV void ph_scan2(const Params& p, int item) {
;     ...
; #pragma unroll 8
;   for (int t = 0; t < CHL; ++t) {
;     float4 a = *(const float4*)(p.a_arr + (row0 + t) * 1024 + ch);
;     float4 bb = *(const float4*)(p.b_arr + (row0 + t) * 1024 + ch);
;     u32x2 xg = *(const u32x2*)(p.z + (row0 + t) * ZLD + CXG + ch);
;     H[0] = a.x * H[0] + bb.x; H[1] = a.y * H[1] + bb.y; H[2] = a.z * H[2] + bb.z; H[3] = a.w * H[3] + bb.w;
;     u32x2 pk;
;     pk[0] = pack2(gelu_exact(bflo(xg[0])) * H[0], gelu_exact(bfhi(xg[0])) * H[1]);
;     pk[1] = pack2(gelu_exact(bflo(xg[1])) * H[2], gelu_exact(bfhi(xg[1])) * H[3]);
;     *(u32x2*)(p.orn + (row0 + t) * 1024 + ch) = pk;
;   }
	v_fma_f32 v161, |v160|, v161, s74
	v_fma_f32 v161, |v160|, v161, s75
	v_fma_f32 v161, |v160|, v161, s76
	v_fma_f32 v161, |v160|, v161, s77
	v_fma_f32 v161, |v160|, v161, |v160|
	v_mul_f32_e32 v162, 0xbfb8aa3b, v161
	v_fma_f32 v163, v161, s78, -v162
	v_rndne_f32_e32 v164, v162
	v_fmac_f32_e32 v163, 0xb2a5705f, v161
	v_sub_f32_e32 v162, v162, v164
	v_add_f32_e32 v162, v162, v163
	v_cvt_i32_f32_e32 v163, v164
	v_exp_f32_e32 v162, v162
	v_cmp_nlt_f32_e32 vcc, s79, v161
	v_ldexp_f32 v162, v162, v163
	s_nop 0
	v_cndmask_b32_e32 v162, 0, v162, vcc
	v_cmp_ngt_f32_e32 vcc, s80, v161
	s_nop 1
	v_cndmask_b32_e32 v161, v3, v162, vcc
	v_sub_f32_e32 v166, 1.0, v161
	v_cmp_lt_f32_e64 vcc, |v160|, 1.0
	s_nop 1
	v_cndmask_b32_e32 v165, v166, v165, vcc
	v_bfi_b32 v165, s81, v165, v160
	v_mul_f32_e32 v161, 0.5, v170
	v_add_f32_e32 v165, 1.0, v165
	v_mul_f32_e32 v161, v161, v165
	v_mul_f32_e32 v178, v161, v6
	v_mul_f32_e32 v160, 0x3f3504f3, v171
	v_mul_f32_e32 v161, v160, v160
	v_fmamk_f32 v162, v161, 0xba1345e1, v8
	v_fmaak_f32 v162, v161, v162, 0xbcdac9b8
	v_fmaak_f32 v162, v161, v162, 0x3de703be
	v_fmaak_f32 v162, v161, v162, 0xbec09330
	v_fmaak_f32 v161, v161, v162, 0x3e0375d0
	v_fma_f32 v165, |v160|, v161, |v160|
	v_fma_f32 v161, |v160|, s72, v9
	v_fma_f32 v161, |v160|, v161, s73
	v_fma_f32 v161, |v160|, v161, s74
	v_fma_f32 v161, |v160|, v161, s75
	v_fma_f32 v161, |v160|, v161, s76
	v_fma_f32 v161, |v160|, v161, s77
	v_fma_f32 v161, |v160|, v161, |v160|
	v_mul_f32_e32 v162, 0xbfb8aa3b, v161
	v_fma_f32 v163, v161, s78, -v162
	v_rndne_f32_e32 v164, v162
	v_fmac_f32_e32 v163, 0xb2a5705f, v161
	v_sub_f32_e32 v162, v162, v164
	v_add_f32_e32 v162, v162, v163
	v_cvt_i32_f32_e32 v163, v164
	v_exp_f32_e32 v162, v162
	v_cmp_nlt_f32_e32 vcc, s79, v161
	v_ldexp_f32 v162, v162, v163
	s_nop 0
	v_cndmask_b32_e32 v162, 0, v162, vcc
	v_cmp_ngt_f32_e32 vcc, s80, v161
	s_nop 1
	v_cndmask_b32_e32 v161, v3, v162, vcc
	v_sub_f32_e32 v166, 1.0, v161
	v_cmp_lt_f32_e64 vcc, |v160|, 1.0
	s_nop 1
	v_cndmask_b32_e32 v165, v166, v165, vcc
	v_bfi_b32 v165, s81, v165, v160
	v_mul_f32_e32 v161, 0.5, v171
	v_add_f32_e32 v165, 1.0, v165
	v_mul_f32_e32 v161, v161, v165
	v_mul_f32_e32 v179, v161, v7
	v_cvt_pk_bf16_f32 v180, v176, v177
	v_cvt_pk_bf16_f32 v181, v178, v179
	global_store_dwordx2 v2, v[180:181], s[34:35]
	s_add_u32 s34, s34, 0x800
	s_addc_u32 s35, s35, 0
	s_waitcnt vmcnt(15)
	v_fma_f32 v4, v110, v4, v114
	v_fma_f32 v5, v111, v5, v115
	v_fma_f32 v6, v112, v6, v116
	v_fma_f32 v7, v113, v7, v117
	v_lshlrev_b32_e32 v168, 16, v118
	v_and_b32_e32 v169, 0xffff0000, v118
	v_lshlrev_b32_e32 v170, 16, v119
	v_and_b32_e32 v171, 0xffff0000, v119
	v_mul_f32_e32 v160, 0x3f3504f3, v168
	v_mul_f32_e32 v161, v160, v160
	v_fmamk_f32 v162, v161, 0xba1345e1, v8
	v_fmaak_f32 v162, v161, v162, 0xbcdac9b8
	v_fmaak_f32 v162, v161, v162, 0x3de703be
	v_fmaak_f32 v162, v161, v162, 0xbec09330
	v_fmaak_f32 v161, v161, v162, 0x3e0375d0
	v_fma_f32 v165, |v160|, v161, |v160|
	v_fma_f32 v161, |v160|, s72, v9
	v_fma_f32 v161, |v160|, v161, s73
	v_fma_f32 v161, |v160|, v161, s74
	v_fma_f32 v161, |v160|, v161, s75
	v_fma_f32 v161, |v160|, v161, s76
	v_fma_f32 v161, |v160|, v161, s77
	v_fma_f32 v161, |v160|, v161, |v160|
	v_mul_f32_e32 v162, 0xbfb8aa3b, v161
	v_fma_f32 v163, v161, s78, -v162
	v_rndne_f32_e32 v164, v162
	v_fmac_f32_e32 v163, 0xb2a5705f, v161
	v_sub_f32_e32 v162, v162, v164
	v_add_f32_e32 v162, v162, v163
	v_cvt_i32_f32_e32 v163, v164
	v_exp_f32_e32 v162, v162
	v_cmp_nlt_f32_e32 vcc, s79, v161
	v_ldexp_f32 v162, v162, v163
	s_nop 0
	v_cndmask_b32_e32 v162, 0, v162, vcc
	v_cmp_ngt_f32_e32 vcc, s80, v161
	s_nop 1
	v_cndmask_b32_e32 v161, v3, v162, vcc
	v_sub_f32_e32 v166, 1.0, v161
	v_cmp_lt_f32_e64 vcc, |v160|, 1.0
	s_nop 1
	v_cndmask_b32_e32 v165, v166, v165, vcc
	v_bfi_b32 v165, s81, v165, v160
	v_mul_f32_e32 v161, 0.5, v168
	v_add_f32_e32 v165, 1.0, v165
	v_mul_f32_e32 v161, v161, v165
	v_mul_f32_e32 v176, v161, v4
	v_mul_f32_e32 v160, 0x3f3504f3, v169
	v_mul_f32_e32 v161, v160, v160
	v_fmamk_f32 v162, v161, 0xba1345e1, v8
	v_fmaak_f32 v162, v161, v162, 0xbcdac9b8
	v_fmaak_f32 v162, v161, v162, 0x3de703be
	v_fmaak_f32 v162, v161, v162, 0xbec09330
	v_fmaak_f32 v161, v161, v162, 0x3e0375d0
	v_fma_f32 v165, |v160|, v161, |v160|
	v_fma_f32 v161, |v160|, s72, v9
	v_fma_f32 v161, |v160|, v161, s73
	v_fma_f32 v161, |v160|, v161, s74
	v_fma_f32 v161, |v160|, v161, s75
	v_fma_f32 v161, |v160|, v161, s76
	v_fma_f32 v161, |v160|, v161, s77
	v_fma_f32 v161, |v160|, v161, |v160|
	v_mul_f32_e32 v162, 0xbfb8aa3b, v161
	v_fma_f32 v163, v161, s78, -v162
	v_rndne_f32_e32 v164, v162
	v_fmac_f32_e32 v163, 0xb2a5705f, v161
	v_sub_f32_e32 v162, v162, v164
	v_add_f32_e32 v162, v162, v163
	v_cvt_i32_f32_e32 v163, v164
	v_exp_f32_e32 v162, v162
	v_cmp_nlt_f32_e32 vcc, s79, v161
	v_ldexp_f32 v162, v162, v163
	s_nop 0
	v_cndmask_b32_e32 v162, 0, v162, vcc
	v_cmp_ngt_f32_e32 vcc, s80, v161
	s_nop 1
	v_cndmask_b32_e32 v161, v3, v162, vcc
	v_sub_f32_e32 v166, 1.0, v161
	v_cmp_lt_f32_e64 vcc, |v160|, 1.0
	s_nop 1
	v_cndmask_b32_e32 v165, v166, v165, vcc
	v_bfi_b32 v165, s81, v165, v160
	v_mul_f32_e32 v161, 0.5, v169
	v_add_f32_e32 v165, 1.0, v165
	v_mul_f32_e32 v161, v161, v165
	v_mul_f32_e32 v177, v161, v5
	v_mul_f32_e32 v160, 0x3f3504f3, v170
	v_mul_f32_e32 v161, v160, v160
	v_fmamk_f32 v162, v161, 0xba1345e1, v8
	v_fmaak_f32 v162, v161, v162, 0xbcdac9b8
	v_fmaak_f32 v162, v161, v162, 0x3de703be
	v_fmaak_f32 v162, v161, v162, 0xbec09330
	v_fmaak_f32 v161, v161, v162, 0x3e0375d0
	v_fma_f32 v165, |v160|, v161, |v160|
	v_fma_f32 v161, |v160|, s72, v9
	v_fma_f32 v161, |v160|, v161, s73
	v_fma_f32 v161, |v160|, v161, s74
; DEV unsigned pack2(float a, float b) { float2v v = {a, b}; return __builtin_bit_cast(unsigned, __builtin_convertvector(v, bf16x2v)); }
; DEV float bflo(unsigned u) { return __uint_as_float(u << 16); }
; DEV float bfhi(unsigned u) { return __uint_as_float(u & 0xffff0000u); }
; DEV float gelu_exact(float v) { return 0.5f * v * (1.f + erff(v * 0.7071067811865476f)); }
; DEV void ph_scan2(const Params& p, int item) {
;     ...
; #pragma unroll 8
;   for (int t = 0; t < CHL; ++t) {
;     float4 a = *(const float4*)(p.a_arr + (row0 + t) * 1024 + ch);
;     float4 bb = *(const float4*)(p.b_arr + (row0 + t) * 1024 + ch);
;     u32x2 xg = *(const u32x2*)(p.z + (row0 + t) * ZLD + CXG + ch);
;     H[0] = a.x * H[0] + bb.x; H[1] = a.y * H[1] + bb.y; H[2] = a.z * H[2] + bb.z; H[3] = a.w * H[3] + bb.w;
;     u32x2 pk;
;     pk[0] = pack2(gelu_exact(bflo(xg[0])) * H[0], gelu_exact(bfhi(xg[0])) * H[1]);
;     pk[1] = pack2(gelu_exact(bflo(xg[1])) * H[2], gelu_exact(bfhi(xg[1])) * H[3]);
;     *(u32x2*)(p.orn + (row0 + t) * 1024 + ch) = pk;
;   }
	v_fma_f32 v161, |v160|, v161, s75
	v_fma_f32 v161, |v160|, v161, s76
	v_fma_f32 v161, |v160|, v161, s77
	v_fma_f32 v161, |v160|, v161, |v160|
	v_mul_f32_e32 v162, 0xbfb8aa3b, v161
	v_fma_f32 v163, v161, s78, -v162
	v_rndne_f32_e32 v164, v162
	v_fmac_f32_e32 v163, 0xb2a5705f, v161
	v_sub_f32_e32 v162, v162, v164
	v_add_f32_e32 v162, v162, v163
	v_cvt_i32_f32_e32 v163, v164
	v_exp_f32_e32 v162, v162
	v_cmp_nlt_f32_e32 vcc, s79, v161
	v_ldexp_f32 v162, v162, v163
	s_nop 0
	v_cndmask_b32_e32 v162, 0, v162, vcc
	v_cmp_ngt_f32_e32 vcc, s80, v161
	s_nop 1
	v_cndmask_b32_e32 v161, v3, v162, vcc
	v_sub_f32_e32 v166, 1.0, v161
	v_cmp_lt_f32_e64 vcc, |v160|, 1.0
	s_nop 1
	v_cndmask_b32_e32 v165, v166, v165, vcc
	v_bfi_b32 v165, s81, v165, v160
	v_mul_f32_e32 v161, 0.5, v170
	v_add_f32_e32 v165, 1.0, v165
	v_mul_f32_e32 v161, v161, v165
	v_mul_f32_e32 v178, v161, v6
	v_mul_f32_e32 v160, 0x3f3504f3, v171
	v_mul_f32_e32 v161, v160, v160
	v_fmamk_f32 v162, v161, 0xba1345e1, v8
	v_fmaak_f32 v162, v161, v162, 0xbcdac9b8
	v_fmaak_f32 v162, v161, v162, 0x3de703be
	v_fmaak_f32 v162, v161, v162, 0xbec09330
	v_fmaak_f32 v161, v161, v162, 0x3e0375d0
	v_fma_f32 v165, |v160|, v161, |v160|
	v_fma_f32 v161, |v160|, s72, v9
	v_fma_f32 v161, |v160|, v161, s73
	v_fma_f32 v161, |v160|, v161, s74
	v_fma_f32 v161, |v160|, v161, s75
	v_fma_f32 v161, |v160|, v161, s76
	v_fma_f32 v161, |v160|, v161, s77
	v_fma_f32 v161, |v160|, v161, |v160|
	v_mul_f32_e32 v162, 0xbfb8aa3b, v161
	v_fma_f32 v163, v161, s78, -v162
	v_rndne_f32_e32 v164, v162
	v_fmac_f32_e32 v163, 0xb2a5705f, v161
	v_sub_f32_e32 v162, v162, v164
	v_add_f32_e32 v162, v162, v163
	v_cvt_i32_f32_e32 v163, v164
	v_exp_f32_e32 v162, v162
	v_cmp_nlt_f32_e32 vcc, s79, v161
	v_ldexp_f32 v162, v162, v163
	s_nop 0
	v_cndmask_b32_e32 v162, 0, v162, vcc
	v_cmp_ngt_f32_e32 vcc, s80, v161
	s_nop 1
	v_cndmask_b32_e32 v161, v3, v162, vcc
	v_sub_f32_e32 v166, 1.0, v161
	v_cmp_lt_f32_e64 vcc, |v160|, 1.0
	s_nop 1
	v_cndmask_b32_e32 v165, v166, v165, vcc
	v_bfi_b32 v165, s81, v165, v160
	v_mul_f32_e32 v161, 0.5, v171
	v_add_f32_e32 v165, 1.0, v165
	v_mul_f32_e32 v161, v161, v165
	v_mul_f32_e32 v179, v161, v7
	v_cvt_pk_bf16_f32 v180, v176, v177
	v_cvt_pk_bf16_f32 v181, v178, v179
	global_store_dwordx2 v2, v[180:181], s[34:35]
	s_add_u32 s34, s34, 0x800
	s_addc_u32 s35, s35, 0
	s_waitcnt vmcnt(13)
	v_fma_f32 v4, v120, v4, v124
	v_fma_f32 v5, v121, v5, v125
	v_fma_f32 v6, v122, v6, v126
	v_fma_f32 v7, v123, v7, v127
	v_lshlrev_b32_e32 v168, 16, v128
	v_and_b32_e32 v169, 0xffff0000, v128
	v_lshlrev_b32_e32 v170, 16, v129
	v_and_b32_e32 v171, 0xffff0000, v129
	v_mul_f32_e32 v160, 0x3f3504f3, v168
	v_mul_f32_e32 v161, v160, v160
	v_fmamk_f32 v162, v161, 0xba1345e1, v8
	v_fmaak_f32 v162, v161, v162, 0xbcdac9b8
	v_fmaak_f32 v162, v161, v162, 0x3de703be
	v_fmaak_f32 v162, v161, v162, 0xbec09330
	v_fmaak_f32 v161, v161, v162, 0x3e0375d0
	v_fma_f32 v165, |v160|, v161, |v160|
	v_fma_f32 v161, |v160|, s72, v9
	v_fma_f32 v161, |v160|, v161, s73
	v_fma_f32 v161, |v160|, v161, s74
	v_fma_f32 v161, |v160|, v161, s75
	v_fma_f32 v161, |v160|, v161, s76
	v_fma_f32 v161, |v160|, v161, s77
	v_fma_f32 v161, |v160|, v161, |v160|
	v_mul_f32_e32 v162, 0xbfb8aa3b, v161
	v_fma_f32 v163, v161, s78, -v162
	v_rndne_f32_e32 v164, v162
	v_fmac_f32_e32 v163, 0xb2a5705f, v161
	v_sub_f32_e32 v162, v162, v164
	v_add_f32_e32 v162, v162, v163
	v_cvt_i32_f32_e32 v163, v164
	v_exp_f32_e32 v162, v162
	v_cmp_nlt_f32_e32 vcc, s79, v161
	v_ldexp_f32 v162, v162, v163
	s_nop 0
	v_cndmask_b32_e32 v162, 0, v162, vcc
	v_cmp_ngt_f32_e32 vcc, s80, v161
	s_nop 1
	v_cndmask_b32_e32 v161, v3, v162, vcc
	v_sub_f32_e32 v166, 1.0, v161
	v_cmp_lt_f32_e64 vcc, |v160|, 1.0
	s_nop 1
	v_cndmask_b32_e32 v165, v166, v165, vcc
	v_bfi_b32 v165, s81, v165, v160
	v_mul_f32_e32 v161, 0.5, v168
	v_add_f32_e32 v165, 1.0, v165
	v_mul_f32_e32 v161, v161, v165
	v_mul_f32_e32 v176, v161, v4
	v_mul_f32_e32 v160, 0x3f3504f3, v169
	v_mul_f32_e32 v161, v160, v160
	v_fmamk_f32 v162, v161, 0xba1345e1, v8
	v_fmaak_f32 v162, v161, v162, 0xbcdac9b8
	v_fmaak_f32 v162, v161, v162, 0x3de703be
	v_fmaak_f32 v162, v161, v162, 0xbec09330
	v_fmaak_f32 v161, v161, v162, 0x3e0375d0
	v_fma_f32 v165, |v160|, v161, |v160|
	v_fma_f32 v161, |v160|, s72, v9
	v_fma_f32 v161, |v160|, v161, s73
	v_fma_f32 v161, |v160|, v161, s74
	v_fma_f32 v161, |v160|, v161, s75
	v_fma_f32 v161, |v160|, v161, s76
	v_fma_f32 v161, |v160|, v161, s77
	v_fma_f32 v161, |v160|, v161, |v160|
	v_mul_f32_e32 v162, 0xbfb8aa3b, v161
	v_fma_f32 v163, v161, s78, -v162
	v_rndne_f32_e32 v164, v162
	v_fmac_f32_e32 v163, 0xb2a5705f, v161
	v_sub_f32_e32 v162, v162, v164
	v_add_f32_e32 v162, v162, v163
	v_cvt_i32_f32_e32 v163, v164
	v_exp_f32_e32 v162, v162
	v_cmp_nlt_f32_e32 vcc, s79, v161
	v_ldexp_f32 v162, v162, v163
	s_nop 0
	v_cndmask_b32_e32 v162, 0, v162, vcc
	v_cmp_ngt_f32_e32 vcc, s80, v161
	s_nop 1
	v_cndmask_b32_e32 v161, v3, v162, vcc
	v_sub_f32_e32 v166, 1.0, v161
	v_cmp_lt_f32_e64 vcc, |v160|, 1.0
	s_nop 1
	v_cndmask_b32_e32 v165, v166, v165, vcc
	v_bfi_b32 v165, s81, v165, v160
	v_mul_f32_e32 v161, 0.5, v169
	v_add_f32_e32 v165, 1.0, v165
	v_mul_f32_e32 v161, v161, v165
	v_mul_f32_e32 v177, v161, v5
	v_mul_f32_e32 v160, 0x3f3504f3, v170
	v_mul_f32_e32 v161, v160, v160
	v_fmamk_f32 v162, v161, 0xba1345e1, v8
	v_fmaak_f32 v162, v161, v162, 0xbcdac9b8
	v_fmaak_f32 v162, v161, v162, 0x3de703be
	v_fmaak_f32 v162, v161, v162, 0xbec09330
	v_fmaak_f32 v161, v161, v162, 0x3e0375d0
	v_fma_f32 v165, |v160|, v161, |v160|
	v_fma_f32 v161, |v160|, s72, v9
	v_fma_f32 v161, |v160|, v161, s73
	v_fma_f32 v161, |v160|, v161, s74
	v_fma_f32 v161, |v160|, v161, s75
; DEV unsigned pack2(float a, float b) { float2v v = {a, b}; return __builtin_bit_cast(unsigned, __builtin_convertvector(v, bf16x2v)); }
; DEV float bflo(unsigned u) { return __uint_as_float(u << 16); }
; DEV float bfhi(unsigned u) { return __uint_as_float(u & 0xffff0000u); }
; DEV float gelu_exact(float v) { return 0.5f * v * (1.f + erff(v * 0.7071067811865476f)); }
; DEV void ph_scan2(const Params& p, int item) {
;     ...
; #pragma unroll 8
;   for (int t = 0; t < CHL; ++t) {
;     float4 a = *(const float4*)(p.a_arr + (row0 + t) * 1024 + ch);
;     float4 bb = *(const float4*)(p.b_arr + (row0 + t) * 1024 + ch);
;     u32x2 xg = *(const u32x2*)(p.z + (row0 + t) * ZLD + CXG + ch);
;     H[0] = a.x * H[0] + bb.x; H[1] = a.y * H[1] + bb.y; H[2] = a.z * H[2] + bb.z; H[3] = a.w * H[3] + bb.w;
;     u32x2 pk;
;     pk[0] = pack2(gelu_exact(bflo(xg[0])) * H[0], gelu_exact(bfhi(xg[0])) * H[1]);
;     pk[1] = pack2(gelu_exact(bflo(xg[1])) * H[2], gelu_exact(bfhi(xg[1])) * H[3]);
;     *(u32x2*)(p.orn + (row0 + t) * 1024 + ch) = pk;
;   }
	v_fma_f32 v161, |v160|, v161, s76
	v_fma_f32 v161, |v160|, v161, s77
	v_fma_f32 v161, |v160|, v161, |v160|
	v_mul_f32_e32 v162, 0xbfb8aa3b, v161
	v_fma_f32 v163, v161, s78, -v162
	v_rndne_f32_e32 v164, v162
	v_fmac_f32_e32 v163, 0xb2a5705f, v161
	v_sub_f32_e32 v162, v162, v164
	v_add_f32_e32 v162, v162, v163
	v_cvt_i32_f32_e32 v163, v164
	v_exp_f32_e32 v162, v162
	v_cmp_nlt_f32_e32 vcc, s79, v161
	v_ldexp_f32 v162, v162, v163
	s_nop 0
	v_cndmask_b32_e32 v162, 0, v162, vcc
	v_cmp_ngt_f32_e32 vcc, s80, v161
	s_nop 1
	v_cndmask_b32_e32 v161, v3, v162, vcc
	v_sub_f32_e32 v166, 1.0, v161
	v_cmp_lt_f32_e64 vcc, |v160|, 1.0
	s_nop 1
	v_cndmask_b32_e32 v165, v166, v165, vcc
	v_bfi_b32 v165, s81, v165, v160
	v_mul_f32_e32 v161, 0.5, v170
	v_add_f32_e32 v165, 1.0, v165
	v_mul_f32_e32 v161, v161, v165
	v_mul_f32_e32 v178, v161, v6
	v_mul_f32_e32 v160, 0x3f3504f3, v171
	v_mul_f32_e32 v161, v160, v160
	v_fmamk_f32 v162, v161, 0xba1345e1, v8
	v_fmaak_f32 v162, v161, v162, 0xbcdac9b8
	v_fmaak_f32 v162, v161, v162, 0x3de703be
	v_fmaak_f32 v162, v161, v162, 0xbec09330
	v_fmaak_f32 v161, v161, v162, 0x3e0375d0
	v_fma_f32 v165, |v160|, v161, |v160|
	v_fma_f32 v161, |v160|, s72, v9
	v_fma_f32 v161, |v160|, v161, s73
	v_fma_f32 v161, |v160|, v161, s74
	v_fma_f32 v161, |v160|, v161, s75
	v_fma_f32 v161, |v160|, v161, s76
	v_fma_f32 v161, |v160|, v161, s77
	v_fma_f32 v161, |v160|, v161, |v160|
	v_mul_f32_e32 v162, 0xbfb8aa3b, v161
	v_fma_f32 v163, v161, s78, -v162
	v_rndne_f32_e32 v164, v162
	v_fmac_f32_e32 v163, 0xb2a5705f, v161
	v_sub_f32_e32 v162, v162, v164
	v_add_f32_e32 v162, v162, v163
	v_cvt_i32_f32_e32 v163, v164
	v_exp_f32_e32 v162, v162
	v_cmp_nlt_f32_e32 vcc, s79, v161
	v_ldexp_f32 v162, v162, v163
	s_nop 0
	v_cndmask_b32_e32 v162, 0, v162, vcc
	v_cmp_ngt_f32_e32 vcc, s80, v161
	s_nop 1
	v_cndmask_b32_e32 v161, v3, v162, vcc
	v_sub_f32_e32 v166, 1.0, v161
	v_cmp_lt_f32_e64 vcc, |v160|, 1.0
	s_nop 1
	v_cndmask_b32_e32 v165, v166, v165, vcc
	v_bfi_b32 v165, s81, v165, v160
	v_mul_f32_e32 v161, 0.5, v171
	v_add_f32_e32 v165, 1.0, v165
	v_mul_f32_e32 v161, v161, v165
	v_mul_f32_e32 v179, v161, v7
	v_cvt_pk_bf16_f32 v180, v176, v177
	v_cvt_pk_bf16_f32 v181, v178, v179
	global_store_dwordx2 v2, v[180:181], s[34:35]
	s_add_u32 s34, s34, 0x800
	s_addc_u32 s35, s35, 0
	s_waitcnt vmcnt(11)
	v_fma_f32 v4, v130, v4, v134
	v_fma_f32 v5, v131, v5, v135
	v_fma_f32 v6, v132, v6, v136
	v_fma_f32 v7, v133, v7, v137
	v_lshlrev_b32_e32 v168, 16, v138
	v_and_b32_e32 v169, 0xffff0000, v138
	v_lshlrev_b32_e32 v170, 16, v139
	v_and_b32_e32 v171, 0xffff0000, v139
	v_mul_f32_e32 v160, 0x3f3504f3, v168
	v_mul_f32_e32 v161, v160, v160
	v_fmamk_f32 v162, v161, 0xba1345e1, v8
	v_fmaak_f32 v162, v161, v162, 0xbcdac9b8
	v_fmaak_f32 v162, v161, v162, 0x3de703be
	v_fmaak_f32 v162, v161, v162, 0xbec09330
	v_fmaak_f32 v161, v161, v162, 0x3e0375d0
	v_fma_f32 v165, |v160|, v161, |v160|
	v_fma_f32 v161, |v160|, s72, v9
	v_fma_f32 v161, |v160|, v161, s73
	v_fma_f32 v161, |v160|, v161, s74
	v_fma_f32 v161, |v160|, v161, s75
	v_fma_f32 v161, |v160|, v161, s76
	v_fma_f32 v161, |v160|, v161, s77
	v_fma_f32 v161, |v160|, v161, |v160|
	v_mul_f32_e32 v162, 0xbfb8aa3b, v161
	v_fma_f32 v163, v161, s78, -v162
	v_rndne_f32_e32 v164, v162
	v_fmac_f32_e32 v163, 0xb2a5705f, v161
	v_sub_f32_e32 v162, v162, v164
	v_add_f32_e32 v162, v162, v163
	v_cvt_i32_f32_e32 v163, v164
	v_exp_f32_e32 v162, v162
	v_cmp_nlt_f32_e32 vcc, s79, v161
	v_ldexp_f32 v162, v162, v163
	s_nop 0
	v_cndmask_b32_e32 v162, 0, v162, vcc
	v_cmp_ngt_f32_e32 vcc, s80, v161
	s_nop 1
	v_cndmask_b32_e32 v161, v3, v162, vcc
	v_sub_f32_e32 v166, 1.0, v161
	v_cmp_lt_f32_e64 vcc, |v160|, 1.0
	s_nop 1
	v_cndmask_b32_e32 v165, v166, v165, vcc
	v_bfi_b32 v165, s81, v165, v160
	v_mul_f32_e32 v161, 0.5, v168
	v_add_f32_e32 v165, 1.0, v165
	v_mul_f32_e32 v161, v161, v165
	v_mul_f32_e32 v176, v161, v4
	v_mul_f32_e32 v160, 0x3f3504f3, v169
	v_mul_f32_e32 v161, v160, v160
	v_fmamk_f32 v162, v161, 0xba1345e1, v8
	v_fmaak_f32 v162, v161, v162, 0xbcdac9b8
	v_fmaak_f32 v162, v161, v162, 0x3de703be
	v_fmaak_f32 v162, v161, v162, 0xbec09330
	v_fmaak_f32 v161, v161, v162, 0x3e0375d0
	v_fma_f32 v165, |v160|, v161, |v160|
	v_fma_f32 v161, |v160|, s72, v9
	v_fma_f32 v161, |v160|, v161, s73
	v_fma_f32 v161, |v160|, v161, s74
	v_fma_f32 v161, |v160|, v161, s75
	v_fma_f32 v161, |v160|, v161, s76
	v_fma_f32 v161, |v160|, v161, s77
	v_fma_f32 v161, |v160|, v161, |v160|
	v_mul_f32_e32 v162, 0xbfb8aa3b, v161
	v_fma_f32 v163, v161, s78, -v162
	v_rndne_f32_e32 v164, v162
	v_fmac_f32_e32 v163, 0xb2a5705f, v161
	v_sub_f32_e32 v162, v162, v164
	v_add_f32_e32 v162, v162, v163
	v_cvt_i32_f32_e32 v163, v164
	v_exp_f32_e32 v162, v162
	v_cmp_nlt_f32_e32 vcc, s79, v161
	v_ldexp_f32 v162, v162, v163
	s_nop 0
	v_cndmask_b32_e32 v162, 0, v162, vcc
	v_cmp_ngt_f32_e32 vcc, s80, v161
	s_nop 1
	v_cndmask_b32_e32 v161, v3, v162, vcc
	v_sub_f32_e32 v166, 1.0, v161
	v_cmp_lt_f32_e64 vcc, |v160|, 1.0
	s_nop 1
	v_cndmask_b32_e32 v165, v166, v165, vcc
	v_bfi_b32 v165, s81, v165, v160
	v_mul_f32_e32 v161, 0.5, v169
	v_add_f32_e32 v165, 1.0, v165
	v_mul_f32_e32 v161, v161, v165
	v_mul_f32_e32 v177, v161, v5
	v_mul_f32_e32 v160, 0x3f3504f3, v170
	v_mul_f32_e32 v161, v160, v160
	v_fmamk_f32 v162, v161, 0xba1345e1, v8
	v_fmaak_f32 v162, v161, v162, 0xbcdac9b8
	v_fmaak_f32 v162, v161, v162, 0x3de703be
	v_fmaak_f32 v162, v161, v162, 0xbec09330
	v_fmaak_f32 v161, v161, v162, 0x3e0375d0
	v_fma_f32 v165, |v160|, v161, |v160|
	v_fma_f32 v161, |v160|, s72, v9
	v_fma_f32 v161, |v160|, v161, s73
	v_fma_f32 v161, |v160|, v161, s74
	v_fma_f32 v161, |v160|, v161, s75
	v_fma_f32 v161, |v160|, v161, s76
; DEV unsigned pack2(float a, float b) { float2v v = {a, b}; return __builtin_bit_cast(unsigned, __builtin_convertvector(v, bf16x2v)); }
; DEV float bflo(unsigned u) { return __uint_as_float(u << 16); }
; DEV float bfhi(unsigned u) { return __uint_as_float(u & 0xffff0000u); }
; DEV float gelu_exact(float v) { return 0.5f * v * (1.f + erff(v * 0.7071067811865476f)); }
; DEV void ph_scan2(const Params& p, int item) {
;     ...
; #pragma unroll 8
;   for (int t = 0; t < CHL; ++t) {
;     float4 a = *(const float4*)(p.a_arr + (row0 + t) * 1024 + ch);
;     float4 bb = *(const float4*)(p.b_arr + (row0 + t) * 1024 + ch);
;     u32x2 xg = *(const u32x2*)(p.z + (row0 + t) * ZLD + CXG + ch);
;     H[0] = a.x * H[0] + bb.x; H[1] = a.y * H[1] + bb.y; H[2] = a.z * H[2] + bb.z; H[3] = a.w * H[3] + bb.w;
;     u32x2 pk;
;     pk[0] = pack2(gelu_exact(bflo(xg[0])) * H[0], gelu_exact(bfhi(xg[0])) * H[1]);
;     pk[1] = pack2(gelu_exact(bflo(xg[1])) * H[2], gelu_exact(bfhi(xg[1])) * H[3]);
;     *(u32x2*)(p.orn + (row0 + t) * 1024 + ch) = pk;
;   }
	v_fma_f32 v161, |v160|, v161, s77
	v_fma_f32 v161, |v160|, v161, |v160|
	v_mul_f32_e32 v162, 0xbfb8aa3b, v161
	v_fma_f32 v163, v161, s78, -v162
	v_rndne_f32_e32 v164, v162
	v_fmac_f32_e32 v163, 0xb2a5705f, v161
	v_sub_f32_e32 v162, v162, v164
	v_add_f32_e32 v162, v162, v163
	v_cvt_i32_f32_e32 v163, v164
	v_exp_f32_e32 v162, v162
	v_cmp_nlt_f32_e32 vcc, s79, v161
	v_ldexp_f32 v162, v162, v163
	s_nop 0
	v_cndmask_b32_e32 v162, 0, v162, vcc
	v_cmp_ngt_f32_e32 vcc, s80, v161
	s_nop 1
	v_cndmask_b32_e32 v161, v3, v162, vcc
	v_sub_f32_e32 v166, 1.0, v161
	v_cmp_lt_f32_e64 vcc, |v160|, 1.0
	s_nop 1
	v_cndmask_b32_e32 v165, v166, v165, vcc
	v_bfi_b32 v165, s81, v165, v160
	v_mul_f32_e32 v161, 0.5, v170
	v_add_f32_e32 v165, 1.0, v165
	v_mul_f32_e32 v161, v161, v165
	v_mul_f32_e32 v178, v161, v6
	v_mul_f32_e32 v160, 0x3f3504f3, v171
	v_mul_f32_e32 v161, v160, v160
	v_fmamk_f32 v162, v161, 0xba1345e1, v8
	v_fmaak_f32 v162, v161, v162, 0xbcdac9b8
	v_fmaak_f32 v162, v161, v162, 0x3de703be
	v_fmaak_f32 v162, v161, v162, 0xbec09330
	v_fmaak_f32 v161, v161, v162, 0x3e0375d0
	v_fma_f32 v165, |v160|, v161, |v160|
	v_fma_f32 v161, |v160|, s72, v9
	v_fma_f32 v161, |v160|, v161, s73
	v_fma_f32 v161, |v160|, v161, s74
	v_fma_f32 v161, |v160|, v161, s75
	v_fma_f32 v161, |v160|, v161, s76
	v_fma_f32 v161, |v160|, v161, s77
	v_fma_f32 v161, |v160|, v161, |v160|
	v_mul_f32_e32 v162, 0xbfb8aa3b, v161
	v_fma_f32 v163, v161, s78, -v162
	v_rndne_f32_e32 v164, v162
	v_fmac_f32_e32 v163, 0xb2a5705f, v161
	v_sub_f32_e32 v162, v162, v164
	v_add_f32_e32 v162, v162, v163
	v_cvt_i32_f32_e32 v163, v164
	v_exp_f32_e32 v162, v162
	v_cmp_nlt_f32_e32 vcc, s79, v161
	v_ldexp_f32 v162, v162, v163
	s_nop 0
	v_cndmask_b32_e32 v162, 0, v162, vcc
	v_cmp_ngt_f32_e32 vcc, s80, v161
	s_nop 1
	v_cndmask_b32_e32 v161, v3, v162, vcc
	v_sub_f32_e32 v166, 1.0, v161
	v_cmp_lt_f32_e64 vcc, |v160|, 1.0
	s_nop 1
	v_cndmask_b32_e32 v165, v166, v165, vcc
	v_bfi_b32 v165, s81, v165, v160
	v_mul_f32_e32 v161, 0.5, v171
	v_add_f32_e32 v165, 1.0, v165
	v_mul_f32_e32 v161, v161, v165
	v_mul_f32_e32 v179, v161, v7
	v_cvt_pk_bf16_f32 v180, v176, v177
	v_cvt_pk_bf16_f32 v181, v178, v179
	global_store_dwordx2 v2, v[180:181], s[34:35]
	s_add_u32 s34, s34, 0x800
	s_addc_u32 s35, s35, 0
	s_waitcnt vmcnt(9)
	v_fma_f32 v4, v140, v4, v144
	v_fma_f32 v5, v141, v5, v145
	v_fma_f32 v6, v142, v6, v146
	v_fma_f32 v7, v143, v7, v147
	v_lshlrev_b32_e32 v168, 16, v148
	v_and_b32_e32 v169, 0xffff0000, v148
	v_lshlrev_b32_e32 v170, 16, v149
	v_and_b32_e32 v171, 0xffff0000, v149
	v_mul_f32_e32 v160, 0x3f3504f3, v168
	v_mul_f32_e32 v161, v160, v160
	v_fmamk_f32 v162, v161, 0xba1345e1, v8
	v_fmaak_f32 v162, v161, v162, 0xbcdac9b8
	v_fmaak_f32 v162, v161, v162, 0x3de703be
	v_fmaak_f32 v162, v161, v162, 0xbec09330
	v_fmaak_f32 v161, v161, v162, 0x3e0375d0
	v_fma_f32 v165, |v160|, v161, |v160|
	v_fma_f32 v161, |v160|, s72, v9
	v_fma_f32 v161, |v160|, v161, s73
	v_fma_f32 v161, |v160|, v161, s74
	v_fma_f32 v161, |v160|, v161, s75
	v_fma_f32 v161, |v160|, v161, s76
	v_fma_f32 v161, |v160|, v161, s77
	v_fma_f32 v161, |v160|, v161, |v160|
	v_mul_f32_e32 v162, 0xbfb8aa3b, v161
	v_fma_f32 v163, v161, s78, -v162
	v_rndne_f32_e32 v164, v162
	v_fmac_f32_e32 v163, 0xb2a5705f, v161
	v_sub_f32_e32 v162, v162, v164
	v_add_f32_e32 v162, v162, v163
	v_cvt_i32_f32_e32 v163, v164
	v_exp_f32_e32 v162, v162
	v_cmp_nlt_f32_e32 vcc, s79, v161
	v_ldexp_f32 v162, v162, v163
	s_nop 0
	v_cndmask_b32_e32 v162, 0, v162, vcc
	v_cmp_ngt_f32_e32 vcc, s80, v161
	s_nop 1
	v_cndmask_b32_e32 v161, v3, v162, vcc
	v_sub_f32_e32 v166, 1.0, v161
	v_cmp_lt_f32_e64 vcc, |v160|, 1.0
	s_nop 1
	v_cndmask_b32_e32 v165, v166, v165, vcc
	v_bfi_b32 v165, s81, v165, v160
	v_mul_f32_e32 v161, 0.5, v168
	v_add_f32_e32 v165, 1.0, v165
	v_mul_f32_e32 v161, v161, v165
	v_mul_f32_e32 v176, v161, v4
	v_mul_f32_e32 v160, 0x3f3504f3, v169
	v_mul_f32_e32 v161, v160, v160
	v_fmamk_f32 v162, v161, 0xba1345e1, v8
	v_fmaak_f32 v162, v161, v162, 0xbcdac9b8
	v_fmaak_f32 v162, v161, v162, 0x3de703be
	v_fmaak_f32 v162, v161, v162, 0xbec09330
	v_fmaak_f32 v161, v161, v162, 0x3e0375d0
	v_fma_f32 v165, |v160|, v161, |v160|
	v_fma_f32 v161, |v160|, s72, v9
	v_fma_f32 v161, |v160|, v161, s73
	v_fma_f32 v161, |v160|, v161, s74
	v_fma_f32 v161, |v160|, v161, s75
	v_fma_f32 v161, |v160|, v161, s76
	v_fma_f32 v161, |v160|, v161, s77
	v_fma_f32 v161, |v160|, v161, |v160|
	v_mul_f32_e32 v162, 0xbfb8aa3b, v161
	v_fma_f32 v163, v161, s78, -v162
	v_rndne_f32_e32 v164, v162
	v_fmac_f32_e32 v163, 0xb2a5705f, v161
	v_sub_f32_e32 v162, v162, v164
	v_add_f32_e32 v162, v162, v163
	v_cvt_i32_f32_e32 v163, v164
	v_exp_f32_e32 v162, v162
	v_cmp_nlt_f32_e32 vcc, s79, v161
	v_ldexp_f32 v162, v162, v163
	s_nop 0
	v_cndmask_b32_e32 v162, 0, v162, vcc
	v_cmp_ngt_f32_e32 vcc, s80, v161
	s_nop 1
	v_cndmask_b32_e32 v161, v3, v162, vcc
	v_sub_f32_e32 v166, 1.0, v161
	v_cmp_lt_f32_e64 vcc, |v160|, 1.0
	s_nop 1
	v_cndmask_b32_e32 v165, v166, v165, vcc
	v_bfi_b32 v165, s81, v165, v160
	v_mul_f32_e32 v161, 0.5, v169
	v_add_f32_e32 v165, 1.0, v165
	v_mul_f32_e32 v161, v161, v165
	v_mul_f32_e32 v177, v161, v5
	v_mul_f32_e32 v160, 0x3f3504f3, v170
	v_mul_f32_e32 v161, v160, v160
	v_fmamk_f32 v162, v161, 0xba1345e1, v8
	v_fmaak_f32 v162, v161, v162, 0xbcdac9b8
	v_fmaak_f32 v162, v161, v162, 0x3de703be
	v_fmaak_f32 v162, v161, v162, 0xbec09330
	v_fmaak_f32 v161, v161, v162, 0x3e0375d0
	v_fma_f32 v165, |v160|, v161, |v160|
	v_fma_f32 v161, |v160|, s72, v9
	v_fma_f32 v161, |v160|, v161, s73
	v_fma_f32 v161, |v160|, v161, s74
	v_fma_f32 v161, |v160|, v161, s75
	v_fma_f32 v161, |v160|, v161, s76
	v_fma_f32 v161, |v160|, v161, s77
; DEV unsigned pack2(float a, float b) { float2v v = {a, b}; return __builtin_bit_cast(unsigned, __builtin_convertvector(v, bf16x2v)); }
; DEV float bflo(unsigned u) { return __uint_as_float(u << 16); }
; DEV float bfhi(unsigned u) { return __uint_as_float(u & 0xffff0000u); }
; DEV float gelu_exact(float v) { return 0.5f * v * (1.f + erff(v * 0.7071067811865476f)); }
; DEV void ph_scan2(const Params& p, int item) {
;     ...
; #pragma unroll 8
;   for (int t = 0; t < CHL; ++t) {
;     float4 a = *(const float4*)(p.a_arr + (row0 + t) * 1024 + ch);
;     float4 bb = *(const float4*)(p.b_arr + (row0 + t) * 1024 + ch);
;     u32x2 xg = *(const u32x2*)(p.z + (row0 + t) * ZLD + CXG + ch);
;     H[0] = a.x * H[0] + bb.x; H[1] = a.y * H[1] + bb.y; H[2] = a.z * H[2] + bb.z; H[3] = a.w * H[3] + bb.w;
;     u32x2 pk;
;     pk[0] = pack2(gelu_exact(bflo(xg[0])) * H[0], gelu_exact(bfhi(xg[0])) * H[1]);
;     pk[1] = pack2(gelu_exact(bflo(xg[1])) * H[2], gelu_exact(bfhi(xg[1])) * H[3]);
;     *(u32x2*)(p.orn + (row0 + t) * 1024 + ch) = pk;
;   }
	v_fma_f32 v161, |v160|, v161, |v160|
	v_mul_f32_e32 v162, 0xbfb8aa3b, v161
	v_fma_f32 v163, v161, s78, -v162
	v_rndne_f32_e32 v164, v162
	v_fmac_f32_e32 v163, 0xb2a5705f, v161
	v_sub_f32_e32 v162, v162, v164
	v_add_f32_e32 v162, v162, v163
	v_cvt_i32_f32_e32 v163, v164
	v_exp_f32_e32 v162, v162
	v_cmp_nlt_f32_e32 vcc, s79, v161
	v_ldexp_f32 v162, v162, v163
	s_nop 0
	v_cndmask_b32_e32 v162, 0, v162, vcc
	v_cmp_ngt_f32_e32 vcc, s80, v161
	s_nop 1
	v_cndmask_b32_e32 v161, v3, v162, vcc
	v_sub_f32_e32 v166, 1.0, v161
	v_cmp_lt_f32_e64 vcc, |v160|, 1.0
	s_nop 1
	v_cndmask_b32_e32 v165, v166, v165, vcc
	v_bfi_b32 v165, s81, v165, v160
	v_mul_f32_e32 v161, 0.5, v170
	v_add_f32_e32 v165, 1.0, v165
	v_mul_f32_e32 v161, v161, v165
	v_mul_f32_e32 v178, v161, v6
	v_mul_f32_e32 v160, 0x3f3504f3, v171
	v_mul_f32_e32 v161, v160, v160
	v_fmamk_f32 v162, v161, 0xba1345e1, v8
	v_fmaak_f32 v162, v161, v162, 0xbcdac9b8
	v_fmaak_f32 v162, v161, v162, 0x3de703be
	v_fmaak_f32 v162, v161, v162, 0xbec09330
	v_fmaak_f32 v161, v161, v162, 0x3e0375d0
	v_fma_f32 v165, |v160|, v161, |v160|
	v_fma_f32 v161, |v160|, s72, v9
	v_fma_f32 v161, |v160|, v161, s73
	v_fma_f32 v161, |v160|, v161, s74
	v_fma_f32 v161, |v160|, v161, s75
	v_fma_f32 v161, |v160|, v161, s76
	v_fma_f32 v161, |v160|, v161, s77
	v_fma_f32 v161, |v160|, v161, |v160|
	v_mul_f32_e32 v162, 0xbfb8aa3b, v161
	v_fma_f32 v163, v161, s78, -v162
	v_rndne_f32_e32 v164, v162
	v_fmac_f32_e32 v163, 0xb2a5705f, v161
	v_sub_f32_e32 v162, v162, v164
	v_add_f32_e32 v162, v162, v163
	v_cvt_i32_f32_e32 v163, v164
	v_exp_f32_e32 v162, v162
	v_cmp_nlt_f32_e32 vcc, s79, v161
	v_ldexp_f32 v162, v162, v163
	s_nop 0
	v_cndmask_b32_e32 v162, 0, v162, vcc
	v_cmp_ngt_f32_e32 vcc, s80, v161
	s_nop 1
	v_cndmask_b32_e32 v161, v3, v162, vcc
	v_sub_f32_e32 v166, 1.0, v161
	v_cmp_lt_f32_e64 vcc, |v160|, 1.0
	s_nop 1
	v_cndmask_b32_e32 v165, v166, v165, vcc
	v_bfi_b32 v165, s81, v165, v160
	v_mul_f32_e32 v161, 0.5, v171
	v_add_f32_e32 v165, 1.0, v165
	v_mul_f32_e32 v161, v161, v165
	v_mul_f32_e32 v179, v161, v7
	v_cvt_pk_bf16_f32 v180, v176, v177
	v_cvt_pk_bf16_f32 v181, v178, v179
	global_store_dwordx2 v2, v[180:181], s[34:35]
	s_add_u32 s34, s34, 0x800
	s_addc_u32 s35, s35, 0
	s_waitcnt vmcnt(7)
; DEV unsigned pack2(float a, float b) { float2v v = {a, b}; return __builtin_bit_cast(unsigned, __builtin_convertvector(v, bf16x2v)); }
; DEV float bflo(unsigned u) { return __uint_as_float(u << 16); }
; DEV float bfhi(unsigned u) { return __uint_as_float(u & 0xffff0000u); }
; DEV float gelu_exact(float v) { return 0.5f * v * (1.f + erff(v * 0.7071067811865476f)); }
; DEV void ph_scan2(const Params& p, int item) {
;     ...
; #pragma unroll 8
;   for (int t = 0; t < CHL; ++t) {
;     float4 a = *(const float4*)(p.a_arr + (row0 + t) * 1024 + ch);
;     float4 bb = *(const float4*)(p.b_arr + (row0 + t) * 1024 + ch);
;     u32x2 xg = *(const u32x2*)(p.z + (row0 + t) * ZLD + CXG + ch);
;     H[0] = a.x * H[0] + bb.x; H[1] = a.y * H[1] + bb.y; H[2] = a.z * H[2] + bb.z; H[3] = a.w * H[3] + bb.w;
;     u32x2 pk;
;     pk[0] = pack2(gelu_exact(bflo(xg[0])) * H[0], gelu_exact(bfhi(xg[0])) * H[1]);
;     pk[1] = pack2(gelu_exact(bflo(xg[1])) * H[2], gelu_exact(bfhi(xg[1])) * H[3]);
;     *(u32x2*)(p.orn + (row0 + t) * 1024 + ch) = pk;
;   }
; __global__ void __launch_bounds__(256, 2) fwd_megakernel(Params p) {
;     ...
;   for (int it = bid; it < B_ * NCH; it += nb) ph_scan2(p, it);
	v_fma_f32 v4, v150, v4, v154
	v_fma_f32 v5, v151, v5, v155
	v_fma_f32 v6, v152, v6, v156
	v_fma_f32 v7, v153, v7, v157
	v_lshlrev_b32_e32 v168, 16, v158
	v_and_b32_e32 v169, 0xffff0000, v158
	v_lshlrev_b32_e32 v170, 16, v159
	v_and_b32_e32 v171, 0xffff0000, v159
	v_mul_f32_e32 v160, 0x3f3504f3, v168
	v_mul_f32_e32 v161, v160, v160
	v_fmamk_f32 v162, v161, 0xba1345e1, v8
	v_fmaak_f32 v162, v161, v162, 0xbcdac9b8
	v_fmaak_f32 v162, v161, v162, 0x3de703be
	v_fmaak_f32 v162, v161, v162, 0xbec09330
	v_fmaak_f32 v161, v161, v162, 0x3e0375d0
	v_fma_f32 v165, |v160|, v161, |v160|
	v_fma_f32 v161, |v160|, s72, v9
	v_fma_f32 v161, |v160|, v161, s73
	v_fma_f32 v161, |v160|, v161, s74
	v_fma_f32 v161, |v160|, v161, s75
	v_fma_f32 v161, |v160|, v161, s76
	v_fma_f32 v161, |v160|, v161, s77
	v_fma_f32 v161, |v160|, v161, |v160|
	v_mul_f32_e32 v162, 0xbfb8aa3b, v161
	v_fma_f32 v163, v161, s78, -v162
	v_rndne_f32_e32 v164, v162
	v_fmac_f32_e32 v163, 0xb2a5705f, v161
	v_sub_f32_e32 v162, v162, v164
	v_add_f32_e32 v162, v162, v163
	v_cvt_i32_f32_e32 v163, v164
	v_exp_f32_e32 v162, v162
	v_cmp_nlt_f32_e32 vcc, s79, v161
	v_ldexp_f32 v162, v162, v163
	s_nop 0
	v_cndmask_b32_e32 v162, 0, v162, vcc
	v_cmp_ngt_f32_e32 vcc, s80, v161
	s_nop 1
	v_cndmask_b32_e32 v161, v3, v162, vcc
	v_sub_f32_e32 v166, 1.0, v161
	v_cmp_lt_f32_e64 vcc, |v160|, 1.0
	s_nop 1
	v_cndmask_b32_e32 v165, v166, v165, vcc
	v_bfi_b32 v165, s81, v165, v160
	v_mul_f32_e32 v161, 0.5, v168
	v_add_f32_e32 v165, 1.0, v165
	v_mul_f32_e32 v161, v161, v165
	v_mul_f32_e32 v176, v161, v4
	v_mul_f32_e32 v160, 0x3f3504f3, v169
	v_mul_f32_e32 v161, v160, v160
	v_fmamk_f32 v162, v161, 0xba1345e1, v8
	v_fmaak_f32 v162, v161, v162, 0xbcdac9b8
	v_fmaak_f32 v162, v161, v162, 0x3de703be
	v_fmaak_f32 v162, v161, v162, 0xbec09330
	v_fmaak_f32 v161, v161, v162, 0x3e0375d0
	v_fma_f32 v165, |v160|, v161, |v160|
	v_fma_f32 v161, |v160|, s72, v9
	v_fma_f32 v161, |v160|, v161, s73
	v_fma_f32 v161, |v160|, v161, s74
	v_fma_f32 v161, |v160|, v161, s75
	v_fma_f32 v161, |v160|, v161, s76
	v_fma_f32 v161, |v160|, v161, s77
	v_fma_f32 v161, |v160|, v161, |v160|
	v_mul_f32_e32 v162, 0xbfb8aa3b, v161
	v_fma_f32 v163, v161, s78, -v162
	v_rndne_f32_e32 v164, v162
	v_fmac_f32_e32 v163, 0xb2a5705f, v161
	v_sub_f32_e32 v162, v162, v164
	v_add_f32_e32 v162, v162, v163
	v_cvt_i32_f32_e32 v163, v164
	v_exp_f32_e32 v162, v162
	v_cmp_nlt_f32_e32 vcc, s79, v161
	v_ldexp_f32 v162, v162, v163
	s_nop 0
	v_cndmask_b32_e32 v162, 0, v162, vcc
	v_cmp_ngt_f32_e32 vcc, s80, v161
	s_nop 1
	v_cndmask_b32_e32 v161, v3, v162, vcc
	v_sub_f32_e32 v166, 1.0, v161
	v_cmp_lt_f32_e64 vcc, |v160|, 1.0
	s_nop 1
	v_cndmask_b32_e32 v165, v166, v165, vcc
	v_bfi_b32 v165, s81, v165, v160
	v_mul_f32_e32 v161, 0.5, v169
	v_add_f32_e32 v165, 1.0, v165
	v_mul_f32_e32 v161, v161, v165
	v_mul_f32_e32 v177, v161, v5
	v_mul_f32_e32 v160, 0x3f3504f3, v170
	v_mul_f32_e32 v161, v160, v160
	v_fmamk_f32 v162, v161, 0xba1345e1, v8
	v_fmaak_f32 v162, v161, v162, 0xbcdac9b8
	v_fmaak_f32 v162, v161, v162, 0x3de703be
	v_fmaak_f32 v162, v161, v162, 0xbec09330
	v_fmaak_f32 v161, v161, v162, 0x3e0375d0
	v_fma_f32 v165, |v160|, v161, |v160|
	v_fma_f32 v161, |v160|, s72, v9
	v_fma_f32 v161, |v160|, v161, s73
	v_fma_f32 v161, |v160|, v161, s74
	v_fma_f32 v161, |v160|, v161, s75
	v_fma_f32 v161, |v160|, v161, s76
	v_fma_f32 v161, |v160|, v161, s77
	v_fma_f32 v161, |v160|, v161, |v160|
	v_mul_f32_e32 v162, 0xbfb8aa3b, v161
	v_fma_f32 v163, v161, s78, -v162
	v_rndne_f32_e32 v164, v162
	v_fmac_f32_e32 v163, 0xb2a5705f, v161
	v_sub_f32_e32 v162, v162, v164
	v_add_f32_e32 v162, v162, v163
	v_cvt_i32_f32_e32 v163, v164
	v_exp_f32_e32 v162, v162
	v_cmp_nlt_f32_e32 vcc, s79, v161
	v_ldexp_f32 v162, v162, v163
	s_nop 0
	v_cndmask_b32_e32 v162, 0, v162, vcc
	v_cmp_ngt_f32_e32 vcc, s80, v161
	s_nop 1
	v_cndmask_b32_e32 v161, v3, v162, vcc
	v_sub_f32_e32 v166, 1.0, v161
	v_cmp_lt_f32_e64 vcc, |v160|, 1.0
	s_nop 1
	v_cndmask_b32_e32 v165, v166, v165, vcc
	v_bfi_b32 v165, s81, v165, v160
	v_mul_f32_e32 v161, 0.5, v170
	v_add_f32_e32 v165, 1.0, v165
	v_mul_f32_e32 v161, v161, v165
	v_mul_f32_e32 v178, v161, v6
	v_mul_f32_e32 v160, 0x3f3504f3, v171
	v_mul_f32_e32 v161, v160, v160
	v_fmamk_f32 v162, v161, 0xba1345e1, v8
	v_fmaak_f32 v162, v161, v162, 0xbcdac9b8
	v_fmaak_f32 v162, v161, v162, 0x3de703be
	v_fmaak_f32 v162, v161, v162, 0xbec09330
	v_fmaak_f32 v161, v161, v162, 0x3e0375d0
	v_fma_f32 v165, |v160|, v161, |v160|
	v_fma_f32 v161, |v160|, s72, v9
	v_fma_f32 v161, |v160|, v161, s73
	v_fma_f32 v161, |v160|, v161, s74
	v_fma_f32 v161, |v160|, v161, s75
	v_fma_f32 v161, |v160|, v161, s76
	v_fma_f32 v161, |v160|, v161, s77
	v_fma_f32 v161, |v160|, v161, |v160|
	v_mul_f32_e32 v162, 0xbfb8aa3b, v161
	v_fma_f32 v163, v161, s78, -v162
	v_rndne_f32_e32 v164, v162
	v_fmac_f32_e32 v163, 0xb2a5705f, v161
	v_sub_f32_e32 v162, v162, v164
	v_add_f32_e32 v162, v162, v163
	v_cvt_i32_f32_e32 v163, v164
	v_exp_f32_e32 v162, v162
	v_cmp_nlt_f32_e32 vcc, s79, v161
	v_ldexp_f32 v162, v162, v163
	s_nop 0
	v_cndmask_b32_e32 v162, 0, v162, vcc
	v_cmp_ngt_f32_e32 vcc, s80, v161
	s_nop 1
	v_cndmask_b32_e32 v161, v3, v162, vcc
	v_sub_f32_e32 v166, 1.0, v161
	v_cmp_lt_f32_e64 vcc, |v160|, 1.0
	s_nop 1
	v_cndmask_b32_e32 v165, v166, v165, vcc
	v_bfi_b32 v165, s81, v165, v160
	v_mul_f32_e32 v161, 0.5, v171
	v_add_f32_e32 v165, 1.0, v165
	v_mul_f32_e32 v161, v161, v165
	v_mul_f32_e32 v179, v161, v7
	v_cvt_pk_bf16_f32 v180, v176, v177
	v_cvt_pk_bf16_f32 v181, v178, v179
	global_store_dwordx2 v2, v[180:181], s[34:35]
	s_add_u32 s34, s34, 0x800
	s_addc_u32 s35, s35, 0
	s_add_u32 s41, s41, 1
	s_cmp_lt_u32 s41, 4
	s_cbranch_scc1 .Lsc_main
	s_cmp_gt_u32 s8, 11
	s_cbranch_scc1 .Lsc_end
	s_cmp_lg_u32 s50, s94
	s_cbranch_scc1 .Lsc_end
	s_sub_u32 s9, 31, s8
	s_lshl_b32 s9, s9, 4
	s_and_b32 s50, s94, 15
	s_add_u32 s50, s50, s9
	s_branch .Lsc_item
